# latency-lean conversion slices (per-matrix constants and pointers persistent in SGPRs, lane constants computed once, next loads issued between the transpose writes and reads); otherwise as v59
# baseline (speedup 1.0000x reference)
; #define LAS __attribute__((address_space(3)))
; #define LDS_WAIT() asm volatile("s_waitcnt lgkmcnt(0)" ::: "memory")
; __device__ __forceinline__ void conv_proc(f32x4 (&v)[2][8], const float* gain, int K, int Kp, int Np, int ilv, bf16* WT, LAS float* scr, int item, int lane) {
;     ...
; #pragma unroll
;     for (int hf = 0; hf < 2; ++hf) {
; #pragma unroll
;         for (int i = 0; i < 8; ++i) { LAS float* d = scr + (8 * i + kr) * 33 + 4 * n4; d[0] = v[hf][i][0]; d[1] = v[hf][i][1]; d[2] = v[hf][i][2]; d[3] = v[hf][i][3]; }
;         LDS_WAIT(); asm volatile("" ::: "memory");
; #pragma unroll
;         for (int j = 0; j < 4; ++j) { const int nn = (lane >> 3) + 8 * j; const LAS float* sp = scr + (8 * c) * 33 + nn;
; __device__ __forceinline__ void convert_mats(Frame& F, int m_lo, int m_hi, int gw, int NGW) {
;     LAS float* scr = (LAS float*)(F.lds + F.wave * 16384);
;     int it = gw, base = 0;
;     for (int mi = m_lo; mi < m_hi; ++mi) {
;         const MatI mt = kMats[mi]; const int cnt = (mt.Kp / 64) * (mt.Np / 64);
;         const float* src = in_ptr(F, mt.in_idx) + mt.src_off; const float* gain = mt.gain_idx >= 0 ? in_ptr(F, mt.gain_idx) + mt.gain_off : nullptr; bf16* dst = (bf16*)((unsigned char*)in_ptr(F, T_WS) + mt.dst_off);
;         while (it < base + cnt) {
;             f32x4 va[2][8], vb[2][8];
;             const int lim = base + cnt, i1 = it + NGW;
;             conv_load(src, mt.K, mt.N, mt.Np, it - base, F.lane, va);
.LBB0_1758:
	s_lshl_b32 s92, s52, 2
	s_lshl_b32 s65, s96, 2
	s_add_u32 s65, s65, s80
	s_sub_u32 s65, s65, 4
	s_sub_u32 s65, s65, s92
	s_mov_b32 s66, 1
	s_mov_b32 s67, 0
	s_mov_b32 s68, 0
	s_mov_b32 s81, 0
	s_mov_b32 s32, 0
	v_mbcnt_lo_u32_b32 v243, -1, 0
	v_mbcnt_hi_u32_b32 v243, -1, v243
	s_sub_u32 s92, s80, 5
	s_mul_i32 s92, s92, 0x2100
	s_add_u32 s92, s92, 0x19200
	s_cmp_eq_u32 s80, 4
	s_cselect_b32 s92, 0x20800, s92
	v_lshrrev_b32_e32 v241, 3, v243
	v_and_b32_e32 v242, 7, v243
	v_mul_u32_u24_e32 v243, 132, v241
	v_lshl_add_u32 v243, v242, 4, v243
	v_add_u32_e32 v238, s92, v243
	v_mul_u32_u24_e32 v243, 0x420, v242
	v_lshl_add_u32 v243, v241, 2, v243
	v_add_u32_e32 v239, s92, v243
	v_lshlrev_b32_e32 v237, 2, v241
	s_cmp_lg_u32 s67, 0
	s_cbranch_scc1 .Lcti_m1
	s_mov_b32 s82, 32
	s_mov_b32 s83, 0x8000000
	s_mov_b32 s84, 0x2000
	s_mov_b32 s85, 0x1000
	s_mov_b32 s86, 0
	s_mov_b32 s87, 1024
	s_add_i32 s92, 0, 0x204a8
	v_mov_b32_e32 v243, s92
	ds_read_b64 v[244:245], v243
	s_waitcnt lgkmcnt(0)
	s_nop 0
	v_readfirstlane_b32 s88, v244
	v_readfirstlane_b32 s89, v245
	s_nop 0
	s_add_u32 s88, s88, 0x0
	s_addc_u32 s89, s89, 0
	s_mov_b64 s[90:91], 0
	s_add_i32 s92, 0, 0x20520
	v_mov_b32_e32 v243, s92
	ds_read_b64 v[244:245], v243
	s_waitcnt lgkmcnt(0)
	s_nop 0
	v_readfirstlane_b32 s74, v244
	v_readfirstlane_b32 s75, v245
	s_nop 0
	s_add_u32 s74, s74, 0xbf00000
	s_addc_u32 s75, s75, 0
	s_branch .Lcti_sdone
.Lcti_m1:
	s_cmp_lg_u32 s67, 1
	s_cbranch_scc1 .Lcti_m2
	s_mov_b32 s82, 176
	s_mov_b32 s83, 0x1745d18
	s_mov_b32 s84, 0xb000
	s_mov_b32 s85, 0x1000
	s_mov_b32 s86, 5632
	s_mov_b32 s87, 5632
	s_add_i32 s92, 0, 0x204d8
	v_mov_b32_e32 v243, s92
	ds_read_b64 v[244:245], v243
	s_waitcnt lgkmcnt(0)
	s_nop 0
	v_readfirstlane_b32 s88, v244
	v_readfirstlane_b32 s89, v245
	s_nop 0
	s_add_u32 s88, s88, 0x5800000
	s_addc_u32 s89, s89, 0
	s_add_i32 s92, 0, 0x204d0
	v_mov_b32_e32 v243, s92
	ds_read_b64 v[244:245], v243
	s_waitcnt lgkmcnt(0)
	s_nop 0
	v_readfirstlane_b32 s90, v244
	v_readfirstlane_b32 s91, v245
	s_nop 0
	s_add_u32 s90, s90, 0x2000
	s_addc_u32 s91, s91, 0
	s_add_i32 s92, 0, 0x20520
	v_mov_b32_e32 v243, s92
	ds_read_b64 v[244:245], v243
	s_waitcnt lgkmcnt(0)
	s_nop 0
	v_readfirstlane_b32 s74, v244
	v_readfirstlane_b32 s75, v245
	s_nop 0
	s_add_u32 s74, s74, 0x11300000
	s_addc_u32 s75, s75, 0
	s_branch .Lcti_sdone
.Lcti_m2:
	s_cmp_lg_u32 s67, 2
	s_cbranch_scc1 .Lcti_m3
	s_mov_b32 s82, 32
	s_mov_b32 s83, 0x8000000
	s_mov_b32 s84, 0x2000
	s_mov_b32 s85, 0x2c00
	s_mov_b32 s86, 0
	s_mov_b32 s87, 2816
	s_add_i32 s92, 0, 0x204f0
	v_mov_b32_e32 v243, s92
	ds_read_b64 v[244:245], v243
	s_waitcnt lgkmcnt(0)
	s_nop 0
	v_readfirstlane_b32 s88, v244
	v_readfirstlane_b32 s89, v245
	s_nop 0
	s_add_u32 s88, s88, 0x2c00000
	s_addc_u32 s89, s89, 0
	s_mov_b64 s[90:91], 0
	s_add_i32 s92, 0, 0x20520
	v_mov_b32_e32 v243, s92
	ds_read_b64 v[244:245], v243
	s_waitcnt lgkmcnt(0)
	s_nop 0
	v_readfirstlane_b32 s74, v244
	v_readfirstlane_b32 s75, v245
	s_nop 0
	s_add_u32 s74, s74, 0x1ad00000
	s_addc_u32 s75, s75, 0
	s_branch .Lcti_sdone
.Lcti_m3:
	s_cmp_lg_u32 s67, 3
	s_cbranch_scc1 .Lcti_m4
	s_mov_b32 s82, 32
	s_mov_b32 s83, 0x8000000
	s_mov_b32 s84, 0x2000
	s_mov_b32 s85, 0x1000
	s_mov_b32 s86, 0
	s_mov_b32 s87, 1024
	s_add_i32 s92, 0, 0x20508
	v_mov_b32_e32 v243, s92
	ds_read_b64 v[244:245], v243
	s_waitcnt lgkmcnt(0)
	s_nop 0
	v_readfirstlane_b32 s88, v244
	v_readfirstlane_b32 s89, v245
	s_nop 0
	s_add_u32 s88, s88, 0x1000000
	s_addc_u32 s89, s89, 0
	s_add_i32 s92, 0, 0x20500
	v_mov_b32_e32 v243, s92
	ds_read_b64 v[244:245], v243
	s_waitcnt lgkmcnt(0)
	s_nop 0
	v_readfirstlane_b32 s90, v244
	v_readfirstlane_b32 s91, v245
	s_nop 0
	s_add_u32 s90, s90, 0x2000
	s_addc_u32 s91, s91, 0
	s_add_i32 s92, 0, 0x20520
	v_mov_b32_e32 v243, s92
	ds_read_b64 v[244:245], v243
	s_waitcnt lgkmcnt(0)
	s_nop 0
	v_readfirstlane_b32 s74, v244
	v_readfirstlane_b32 s75, v245
	s_nop 0
	s_add_u32 s74, s74, 0x1f700000
	s_addc_u32 s75, s75, 0
	s_branch .Lcti_sdone
; #define LAS __attribute__((address_space(3)))
; __device__ __forceinline__ void convert_mats(Frame& F, int m_lo, int m_hi, int gw, int NGW) {
;     LAS float* scr = (LAS float*)(F.lds + F.wave * 16384);
;     int it = gw, base = 0;
;     for (int mi = m_lo; mi < m_hi; ++mi) {
;         const MatI mt = kMats[mi]; const int cnt = (mt.Kp / 64) * (mt.Np / 64);
;         const float* src = in_ptr(F, mt.in_idx) + mt.src_off; const float* gain = mt.gain_idx >= 0 ? in_ptr(F, mt.gain_idx) + mt.gain_off : nullptr; bf16* dst = (bf16*)((unsigned char*)in_ptr(F, T_WS) + mt.dst_off);
.Lcti_m4:
	s_cmp_lg_u32 s67, 4
	s_cbranch_scc1 .Lcti_m5
	s_mov_b32 s82, 96
	s_mov_b32 s83, 0x2aaaaab
	s_mov_b32 s84, 0x6000
	s_mov_b32 s85, 0x1000
	s_mov_b32 s86, 0
	s_mov_b32 s87, 3072
	s_add_i32 s92, 0, 0x204b8
	v_mov_b32_e32 v243, s92
	ds_read_b64 v[244:245], v243
	s_waitcnt lgkmcnt(0)
	s_nop 0
	v_readfirstlane_b32 s88, v244
	v_readfirstlane_b32 s89, v245
	s_nop 0
	s_add_u32 s88, s88, 0x0
	s_addc_u32 s89, s89, 0
	s_add_i32 s92, 0, 0x204b0
	v_mov_b32_e32 v243, s92
	ds_read_b64 v[244:245], v243
	s_waitcnt lgkmcnt(0)
	s_nop 0
	v_readfirstlane_b32 s90, v244
	v_readfirstlane_b32 s91, v245
	s_nop 0
	s_add_u32 s90, s90, 0x0
	s_addc_u32 s91, s91, 0
	s_add_i32 s92, 0, 0x20520
	v_mov_b32_e32 v243, s92
	ds_read_b64 v[244:245], v243
	s_waitcnt lgkmcnt(0)
	s_nop 0
	v_readfirstlane_b32 s74, v244
	v_readfirstlane_b32 s75, v245
	s_nop 0
	s_add_u32 s74, s74, 0xc700000
	s_addc_u32 s75, s75, 0
	s_branch .Lcti_sdone
.Lcti_m5:
	s_cmp_lg_u32 s67, 5
	s_cbranch_scc1 .Lcti_m6
	s_mov_b32 s82, 32
	s_mov_b32 s83, 0x8000000
	s_mov_b32 s84, 0x2000
	s_mov_b32 s85, 0x1000
	s_mov_b32 s86, 0
	s_mov_b32 s87, 1024
	s_add_i32 s92, 0, 0x204c8
	v_mov_b32_e32 v243, s92
	ds_read_b64 v[244:245], v243
	s_waitcnt lgkmcnt(0)
	s_nop 0
	v_readfirstlane_b32 s88, v244
	v_readfirstlane_b32 s89, v245
	s_nop 0
	s_add_u32 s88, s88, 0x0
	s_addc_u32 s89, s89, 0
	s_mov_b64 s[90:91], 0
	s_add_i32 s92, 0, 0x20520
	v_mov_b32_e32 v243, s92
	ds_read_b64 v[244:245], v243
	s_waitcnt lgkmcnt(0)
	s_nop 0
	v_readfirstlane_b32 s74, v244
	v_readfirstlane_b32 s75, v245
	s_nop 0
	s_add_u32 s74, s74, 0xdf00000
	s_addc_u32 s75, s75, 0
	s_branch .Lcti_sdone
.Lcti_m6:
	s_cmp_lg_u32 s67, 6
	s_cbranch_scc1 .Lcti_m7
	s_mov_b32 s82, 32
	s_mov_b32 s83, 0x8000000
	s_mov_b32 s84, 0x2000
	s_mov_b32 s85, 0x2c00
	s_mov_b32 s86, 0
	s_mov_b32 s87, 2816
	s_add_i32 s92, 0, 0x204f0
	v_mov_b32_e32 v243, s92
	ds_read_b64 v[244:245], v243
	s_waitcnt lgkmcnt(0)
	s_nop 0
	v_readfirstlane_b32 s88, v244
	v_readfirstlane_b32 s89, v245
	s_nop 0
	s_add_u32 s88, s88, 0x5800000
	s_addc_u32 s89, s89, 0
	s_mov_b64 s[90:91], 0
	s_add_i32 s92, 0, 0x20520
	v_mov_b32_e32 v243, s92
	ds_read_b64 v[244:245], v243
	s_waitcnt lgkmcnt(0)
	s_nop 0
	v_readfirstlane_b32 s74, v244
	v_readfirstlane_b32 s75, v245
	s_nop 0
	s_add_u32 s74, s74, 0x1c300000
	s_addc_u32 s75, s75, 0
	s_branch .Lcti_sdone
.Lcti_m7:
	s_mov_b32 s82, 288
	s_mov_b32 s83, 0xe38e39
	s_mov_b32 s84, 0x12000
	s_mov_b32 s85, 0x1000
	s_mov_b32 s86, 0
	s_mov_b32 s87, 9216
	s_add_i32 s92, 0, 0x20418
	v_mov_b32_e32 v243, s92
	ds_read_b64 v[244:245], v243
	s_waitcnt lgkmcnt(0)
	s_nop 0
	v_readfirstlane_b32 s88, v244
	v_readfirstlane_b32 s89, v245
	s_nop 0
	s_add_u32 s88, s88, 0x9000000
	s_addc_u32 s89, s89, 0
	s_add_i32 s92, 0, 0x20410
	v_mov_b32_e32 v243, s92
	ds_read_b64 v[244:245], v243
	s_waitcnt lgkmcnt(0)
	s_nop 0
	v_readfirstlane_b32 s90, v244
	v_readfirstlane_b32 s91, v245
	s_nop 0
	s_add_u32 s90, s90, 0x2000
	s_addc_u32 s91, s91, 0
	s_add_i32 s92, 0, 0x20520
	v_mov_b32_e32 v243, s92
	ds_read_b64 v[244:245], v243
	s_waitcnt lgkmcnt(0)
	s_nop 0
	v_readfirstlane_b32 s74, v244
	v_readfirstlane_b32 s75, v245
	s_nop 0
	s_add_u32 s74, s74, 0x4900000
	s_addc_u32 s75, s75, 0

; #define LAS __attribute__((address_space(3)))
; #define LDS_WAIT() asm volatile("s_waitcnt lgkmcnt(0)" ::: "memory")
; __device__ __forceinline__ void conv_proc(f32x4 (&v)[2][8], const float* gain, int K, int Kp, int Np, int ilv, bf16* WT, LAS float* scr, int item, int lane) {
;     ...
;     const int c = lane & 7;
; #pragma unroll
;     for (int hf = 0; hf < 2; ++hf) {
; #pragma unroll
;         for (int i = 0; i < 8; ++i) { LAS float* d = scr + (8 * i + kr) * 33 + 4 * n4; d[0] = v[hf][i][0]; d[1] = v[hf][i][1]; d[2] = v[hf][i][2]; d[3] = v[hf][i][3]; }
;         LDS_WAIT(); asm volatile("" ::: "memory");
; #pragma unroll
;         for (int j = 0; j < 4; ++j) { const int nn = (lane >> 3) + 8 * j; const LAS float* sp = scr + (8 * c) * 33 + nn;
.LBB0_1787:
	s_cmp_eq_u32 s81, 0
	s_cbranch_scc1 .Lcta_idle
	s_and_b32 s92, s81, 0x7fffffff
	v_mul_lo_u32 v243, v241, s92
	v_lshl_add_u32 v240, v242, 4, v243
	s_cmp_eq_u32 s32, 1
	s_cbranch_scc0 .Lcta_w0
	s_waitcnt vmcnt(10)
	s_branch .Lcta_wd

; #define LAS __attribute__((address_space(3)))
; #define LDS_WAIT() asm volatile("s_waitcnt lgkmcnt(0)" ::: "memory")
; __device__ __forceinline__ void conv_proc(f32x4 (&v)[2][8], const float* gain, int K, int Kp, int Np, int ilv, bf16* WT, LAS float* scr, int item, int lane) {
;     ...
;     if (gain) {
; #pragma unroll
;         for (int i = 0; i < 8; ++i) { const int k = k0 + 8 * i + kr; const float g = k < K ? gain[k] : 0.f; v[0][i] *= g; v[1][i] *= g; } }
;     const int c = lane & 7;
; #pragma unroll
;     for (int hf = 0; hf < 2; ++hf) {
; #pragma unroll
;         for (int i = 0; i < 8; ++i) { LAS float* d = scr + (8 * i + kr) * 33 + 4 * n4; d[0] = v[hf][i][0]; d[1] = v[hf][i][1]; d[2] = v[hf][i][2]; d[3] = v[hf][i][3]; }
;         LDS_WAIT(); asm volatile("" ::: "memory");
; #pragma unroll
;         for (int j = 0; j < 4; ++j) { const int nn = (lane >> 3) + 8 * j; const LAS float* sp = scr + (8 * c) * 33 + nn;
; __device__ __forceinline__ void convert_mats(Frame& F, int m_lo, int m_hi, int gw, int NGW) {
;     ...
;     for (int mi = m_lo; mi < m_hi; ++mi) {
;         const MatI mt = kMats[mi]; const int cnt = (mt.Kp / 64) * (mt.Np / 64);
;         const float* src = in_ptr(F, mt.in_idx) + mt.src_off; const float* gain = mt.gain_idx >= 0 ? in_ptr(F, mt.gain_idx) + mt.gain_off : nullptr; bf16* dst = (bf16*)((unsigned char*)in_ptr(F, T_WS) + mt.dst_off);
;         while (it < base + cnt) {
;             f32x4 va[2][8], vb[2][8];
;             const int lim = base + cnt, i1 = it + NGW;
;             conv_load(src, mt.K, mt.N, mt.Np, it - base, F.lane, va);
;             if (i1 < lim) conv_load(src, mt.K, mt.N, mt.Np, i1 - base, F.lane, vb);
;             conv_proc(va, gain, mt.K, mt.Kp, mt.Np, mt.ilv, dst, scr, it - base, F.lane);
;             if (i1 < lim) conv_proc(vb, gain, mt.K, mt.Kp, mt.Np, mt.ilv, dst, scr, i1 - base, F.lane);
;             it = (i1 < lim) ? i1 + NGW : i1;
.Lcta_wd:
	s_bitcmp0_b32 s81, 31
	s_cbranch_scc1 .Lcta_nogain
	v_pk_mul_f32 v[188:189], v[188:189], v[220:221] op_sel_hi:[1,0]
	v_pk_mul_f32 v[190:191], v[190:191], v[220:221] op_sel_hi:[1,0]
	v_pk_mul_f32 v[192:193], v[192:193], v[220:221] op_sel:[0,1] op_sel_hi:[1,1]
	v_pk_mul_f32 v[194:195], v[194:195], v[220:221] op_sel:[0,1] op_sel_hi:[1,1]
	v_pk_mul_f32 v[196:197], v[196:197], v[222:223] op_sel_hi:[1,0]
	v_pk_mul_f32 v[198:199], v[198:199], v[222:223] op_sel_hi:[1,0]
	v_pk_mul_f32 v[200:201], v[200:201], v[222:223] op_sel:[0,1] op_sel_hi:[1,1]
	v_pk_mul_f32 v[202:203], v[202:203], v[222:223] op_sel:[0,1] op_sel_hi:[1,1]
	v_pk_mul_f32 v[204:205], v[204:205], v[224:225] op_sel_hi:[1,0]
	v_pk_mul_f32 v[206:207], v[206:207], v[224:225] op_sel_hi:[1,0]
	v_pk_mul_f32 v[208:209], v[208:209], v[224:225] op_sel:[0,1] op_sel_hi:[1,1]
	v_pk_mul_f32 v[210:211], v[210:211], v[224:225] op_sel:[0,1] op_sel_hi:[1,1]
	v_pk_mul_f32 v[212:213], v[212:213], v[226:227] op_sel_hi:[1,0]
	v_pk_mul_f32 v[214:215], v[214:215], v[226:227] op_sel_hi:[1,0]
	v_pk_mul_f32 v[216:217], v[216:217], v[226:227] op_sel:[0,1] op_sel_hi:[1,1]
	v_pk_mul_f32 v[218:219], v[218:219], v[226:227] op_sel:[0,1] op_sel_hi:[1,1]
.Lcta_nogain:
	ds_write_b32 v238, v188 offset:0
	ds_write_b32 v238, v189 offset:4
	ds_write_b32 v238, v190 offset:8
	ds_write_b32 v238, v191 offset:12
	ds_write_b32 v238, v192 offset:1056
	ds_write_b32 v238, v193 offset:1060
	ds_write_b32 v238, v194 offset:1064
	ds_write_b32 v238, v195 offset:1068
	ds_write_b32 v238, v196 offset:2112
	ds_write_b32 v238, v197 offset:2116
	ds_write_b32 v238, v198 offset:2120
	ds_write_b32 v238, v199 offset:2124
	ds_write_b32 v238, v200 offset:3168
	ds_write_b32 v238, v201 offset:3172
	ds_write_b32 v238, v202 offset:3176
	ds_write_b32 v238, v203 offset:3180
	ds_write_b32 v238, v204 offset:4224
	ds_write_b32 v238, v205 offset:4228
	ds_write_b32 v238, v206 offset:4232
	ds_write_b32 v238, v207 offset:4236
	ds_write_b32 v238, v208 offset:5280
	ds_write_b32 v238, v209 offset:5284
	ds_write_b32 v238, v210 offset:5288
	ds_write_b32 v238, v211 offset:5292
	ds_write_b32 v238, v212 offset:6336
	ds_write_b32 v238, v213 offset:6340
	ds_write_b32 v238, v214 offset:6344
	ds_write_b32 v238, v215 offset:6348
	ds_write_b32 v238, v216 offset:7392
	ds_write_b32 v238, v217 offset:7396
	ds_write_b32 v238, v218 offset:7400
	ds_write_b32 v238, v219 offset:7404
	s_mov_b32 s69, 0
	s_cmp_eq_u32 s66, 0
	s_cbranch_scc0 .Lctax_nexttile
	s_mov_b32 s66, 1
	s_branch .Lctax_find
.Lctax_nexttile:
	s_mov_b32 s66, 0
	s_lshl_b32 s92, s52, 2
	s_add_u32 s65, s65, s92
.Lctax_find:
	s_cmp_lt_u32 s67, 8
	s_cbranch_scc0 .Lctax_end
	s_add_u32 s92, s68, s87
	s_cmp_lt_u32 s65, s92
	s_cbranch_scc1 .Lctax_found
	s_mov_b32 s68, s92
	s_add_u32 s67, s67, 1
	s_cmp_lt_u32 s67, 8
	s_cbranch_scc0 .Lctax_end
	s_cmp_lg_u32 s67, 0
	s_cbranch_scc1 .Lctax_m1
	s_mov_b32 s82, 32
	s_mov_b32 s83, 0x8000000
	s_mov_b32 s84, 0x2000
	s_mov_b32 s85, 0x1000
	s_mov_b32 s86, 0
	s_mov_b32 s87, 1024
	s_add_i32 s92, 0, 0x204a8
	v_mov_b32_e32 v243, s92
	ds_read_b64 v[244:245], v243
	s_waitcnt lgkmcnt(0)
	s_nop 0
	v_readfirstlane_b32 s88, v244
	v_readfirstlane_b32 s89, v245
	s_nop 0
	s_add_u32 s88, s88, 0x0
	s_addc_u32 s89, s89, 0
	s_mov_b64 s[90:91], 0
	s_add_i32 s92, 0, 0x20520
	v_mov_b32_e32 v243, s92
	ds_read_b64 v[244:245], v243
	s_waitcnt lgkmcnt(0)
	s_nop 0
	v_readfirstlane_b32 s74, v244
	v_readfirstlane_b32 s75, v245
	s_nop 0
	s_add_u32 s74, s74, 0xbf00000
	s_addc_u32 s75, s75, 0
	s_branch .Lctax_sdone

; #define GAS __attribute__((address_space(1)))
; #define LAS __attribute__((address_space(3)))
; #define LDS_WAIT() asm volatile("s_waitcnt lgkmcnt(0)" ::: "memory")
; __device__ __forceinline__ unsigned pk2(float lo, float hi) { unsigned r; asm("v_cvt_pk_bf16_f32 %0, %1, %2" : "=v"(r) : "v"(lo), "v"(hi)); return r; }
; __device__ __forceinline__ void conv_load(const float* W, int K, int N, int Np, int item, int lane, f32x4 (&v)[2][8]) {
;     const int nblk = Np / 64, kb = item / nblk, nb = item % nblk, k0 = 64 * kb, n0 = 64 * nb;
;     const int kr = lane >> 3, n4 = lane & 7;
; #pragma unroll
;     for (int hf = 0; hf < 2; ++hf)
; #pragma unroll
;         for (int i = 0; i < 8; ++i) { const int k = k0 + 8 * i + kr, n = n0 + 32 * hf + 4 * n4;
;             v[hf][i] = (k < K && n < N) ? __builtin_nontemporal_load((const GAS f32x4*)(W + (size_t)k * N + n)) : (f32x4){0.f, 0.f, 0.f, 0.f}; }
; }
; __device__ __forceinline__ void conv_proc(f32x4 (&v)[2][8], const float* gain, int K, int Kp, int Np, int ilv, bf16* WT, LAS float* scr, int item, int lane) {
;     const int nblk = Np / 64, kb = item / nblk, nb = item % nblk, k0 = 64 * kb, n0 = 64 * nb;
;     const int d0 = ilv ? (((n0 % ilv) >> 7) * 256 + (n0 / ilv) * 128 + ((n0 % ilv) & 127)) : n0;
;     const int kr = lane >> 3, n4 = lane & 7;
;     if (gain) {
; #pragma unroll
;         for (int i = 0; i < 8; ++i) { const int k = k0 + 8 * i + kr; const float g = k < K ? gain[k] : 0.f; v[0][i] *= g; v[1][i] *= g; } }
;     const int c = lane & 7;
; #pragma unroll
;     for (int hf = 0; hf < 2; ++hf) {
; #pragma unroll
;         for (int i = 0; i < 8; ++i) { LAS float* d = scr + (8 * i + kr) * 33 + 4 * n4; d[0] = v[hf][i][0]; d[1] = v[hf][i][1]; d[2] = v[hf][i][2]; d[3] = v[hf][i][3]; }
;         LDS_WAIT(); asm volatile("" ::: "memory");
; #pragma unroll
;         for (int j = 0; j < 4; ++j) { const int nn = (lane >> 3) + 8 * j; const LAS float* sp = scr + (8 * c) * 33 + nn;
;             v4u o; o.x = pk2(sp[0 * 33], sp[1 * 33]); o.y = pk2(sp[2 * 33], sp[3 * 33]); o.z = pk2(sp[4 * 33], sp[5 * 33]); o.w = pk2(sp[6 * 33], sp[7 * 33]);
;             __builtin_nontemporal_store(o, (GAS v4u*)(WT + (size_t)(d0 + 32 * hf + nn) * Kp + k0 + 8 * c)); }
;         LDS_WAIT(); asm volatile("" ::: "memory");
;     }
; }
.Lctax_found:
	s_sub_u32 s94, s65, s68
	s_mul_hi_u32 s95, s94, s83
	s_mul_i32 s97, s95, s82
	s_sub_u32 s94, s94, s97
	s_lshl_b32 s97, s84, 6
	s_mul_i32 s97, s97, s95
	s_lshl_b32 s92, s94, 8
	s_add_u32 s97, s97, s92
	s_lshl_b32 s92, s66, 7
	s_add_u32 s97, s97, s92
	s_add_u32 s76, s88, s97
	s_addc_u32 s77, s89, 0
	s_lshl_b32 s94, s94, 6
	s_cmp_eq_u32 s86, 0
	s_cbranch_scc1 .Lctax_noilv
	s_cmp_ge_u32 s94, s86
	s_cselect_b32 s97, s86, 0
	s_cselect_b32 s92, 128, 0
	s_sub_u32 s94, s94, s97
	s_lshr_b32 s97, s94, 7
	s_lshl_b32 s97, s97, 8
	s_and_b32 s94, s94, 127
	s_add_u32 s94, s94, s97
	s_add_u32 s94, s94, s92
.Lctax_noilv:
	s_lshl_b32 s92, s66, 5
	s_add_u32 s94, s94, s92
	s_mul_i32 s94, s94, s85
	s_lshl_b32 s92, s95, 7
	s_add_u32 s94, s94, s92
	s_add_u32 s70, s74, s94
	s_addc_u32 s71, s75, 0
	s_mov_b32 s69, s85
	v_mul_lo_u32 v243, v241, s84
	v_lshl_add_u32 v236, v242, 4, v243
	s_lshl_b32 s97, s84, 3
	global_load_dwordx4 v[188:191], v236, s[76:77] nt
	s_add_u32 s76, s76, s97
	s_addc_u32 s77, s77, 0
	global_load_dwordx4 v[192:195], v236, s[76:77] nt
	s_add_u32 s76, s76, s97
	s_addc_u32 s77, s77, 0
	global_load_dwordx4 v[196:199], v236, s[76:77] nt
	s_add_u32 s76, s76, s97
	s_addc_u32 s77, s77, 0
	global_load_dwordx4 v[200:203], v236, s[76:77] nt
	s_add_u32 s76, s76, s97
	s_addc_u32 s77, s77, 0
	global_load_dwordx4 v[204:207], v236, s[76:77] nt
	s_add_u32 s76, s76, s97
	s_addc_u32 s77, s77, 0
	global_load_dwordx4 v[208:211], v236, s[76:77] nt
	s_add_u32 s76, s76, s97
	s_addc_u32 s77, s77, 0
	global_load_dwordx4 v[212:215], v236, s[76:77] nt
	s_add_u32 s76, s76, s97
	s_addc_u32 s77, s77, 0
	global_load_dwordx4 v[216:219], v236, s[76:77] nt
	s_cmp_eq_u32 s91, 0
	s_cbranch_scc1 .Lctax_end
	s_bitset1_b32 s69, 31
	s_cmp_eq_u32 s66, 0
	s_cbranch_scc0 .Lctax_end
	s_lshl_b32 s92, s95, 8
	s_add_u32 s92, s90, s92
	s_addc_u32 s93, s91, 0
	global_load_dword v220, v237, s[92:93]
	global_load_dword v221, v237, s[92:93] offset:32
	global_load_dword v222, v237, s[92:93] offset:64
	global_load_dword v223, v237, s[92:93] offset:96
	global_load_dword v224, v237, s[92:93] offset:128
	global_load_dword v225, v237, s[92:93] offset:160
	global_load_dword v226, v237, s[92:93] offset:192
	global_load_dword v227, v237, s[92:93] offset:224
.Lctax_end:
	s_and_b32 s97, s81, 0x7fffffff
	s_waitcnt lgkmcnt(0)
	ds_read2_b32 v[148:149], v239 offset0:0 offset1:33
	ds_read2_b32 v[150:151], v239 offset0:66 offset1:99
	ds_read2_b32 v[152:153], v239 offset0:132 offset1:165
	ds_read2_b32 v[154:155], v239 offset0:198 offset1:231
	ds_read2_b32 v[156:157], v239 offset0:8 offset1:41
	ds_read2_b32 v[158:159], v239 offset0:74 offset1:107
	ds_read2_b32 v[160:161], v239 offset0:140 offset1:173
	ds_read2_b32 v[162:163], v239 offset0:206 offset1:239
	s_waitcnt lgkmcnt(4)
	v_cvt_pk_bf16_f32 v228, v148, v149
	v_cvt_pk_bf16_f32 v229, v150, v151
	v_cvt_pk_bf16_f32 v230, v152, v153
	v_cvt_pk_bf16_f32 v231, v154, v155
	global_store_dwordx4 v240, v[228:231], s[78:79] nt
	ds_read2_b32 v[148:149], v239 offset0:16 offset1:49
	ds_read2_b32 v[150:151], v239 offset0:82 offset1:115
	ds_read2_b32 v[152:153], v239 offset0:148 offset1:181
	ds_read2_b32 v[154:155], v239 offset0:214 offset1:247
	s_waitcnt lgkmcnt(4)
	v_cvt_pk_bf16_f32 v232, v156, v157
	v_cvt_pk_bf16_f32 v233, v158, v159
	v_cvt_pk_bf16_f32 v234, v160, v161
	v_cvt_pk_bf16_f32 v235, v162, v163
	s_mul_i32 s92, s97, 8
	s_add_u32 s94, s78, s92
	s_addc_u32 s95, s79, 0
	global_store_dwordx4 v240, v[232:235], s[94:95] nt
	ds_read2_b32 v[156:157], v239 offset0:24 offset1:57
	ds_read2_b32 v[158:159], v239 offset0:90 offset1:123
	ds_read2_b32 v[160:161], v239 offset0:156 offset1:189
	ds_read2_b32 v[162:163], v239 offset0:222 offset1:255
	s_waitcnt lgkmcnt(4)
	v_cvt_pk_bf16_f32 v228, v148, v149
	v_cvt_pk_bf16_f32 v229, v150, v151
	v_cvt_pk_bf16_f32 v230, v152, v153
	v_cvt_pk_bf16_f32 v231, v154, v155
	s_mul_i32 s92, s97, 16
	s_add_u32 s94, s78, s92
	s_addc_u32 s95, s79, 0
	global_store_dwordx4 v240, v[228:231], s[94:95] nt
	s_waitcnt lgkmcnt(0)
	v_cvt_pk_bf16_f32 v232, v156, v157
	v_cvt_pk_bf16_f32 v233, v158, v159
	v_cvt_pk_bf16_f32 v234, v160, v161
	v_cvt_pk_bf16_f32 v235, v162, v163
	s_mul_i32 s92, s97, 24
	s_add_u32 s94, s78, s92
	s_addc_u32 s95, s79, 0
	global_store_dwordx4 v240, v[232:235], s[94:95] nt
	s_branch .Lcta_fin
.Lcta_idle:
	s_mov_b32 s69, 0
	s_cmp_eq_u32 s66, 0
	s_cbranch_scc0 .Lctay_nexttile
	s_mov_b32 s66, 1
	s_branch .Lctay_find

.Lctay_end:
.Lcta_fin:
	s_mov_b64 s[78:79], s[70:71]
	s_mov_b32 s81, s69
	s_mov_b32 s32, 0
	ds_read_b128 v[28:31], v169
	v_lshl_add_u64 v[86:87], s[10:11], 0, v[76:77]
	v_add_co_u32_e32 v34, vcc, s53, v86
	s_waitcnt lgkmcnt(0)
	v_cvt_pk_bf16_f32 v32, v28, v29
	v_cvt_pk_bf16_f32 v33, v30, v31
	v_mul_f32_e32 v79, v30, v30
	v_addc_co_u32_e32 v35, vcc, 0, v87, vcc
	global_store_dwordx2 v[34:35], v[32:33], off
	v_mul_f32_e32 v33, v28, v28
	v_mul_f32_e32 v35, v29, v29
	v_mul_f32_e32 v81, v31, v31
	v_mov_b32_e32 v32, v28
	v_mov_b32_e32 v34, v29
	v_mov_b32_e32 v78, v30
	v_mov_b32_e32 v80, v31
	v_pk_add_f32 v[28:29], v[32:33], v[34:35]
	v_pk_add_f32 v[30:31], v[78:79], v[80:81]
	v_lshl_add_u64 v[84:85], s[10:11], 0, v[74:75]
	v_pk_add_f32 v[28:29], v[28:29], v[30:31]
	s_nop 1
	v_mov_b32_dpp v30, v28 quad_perm:[1,0,3,2] row_mask:0xf bank_mask:0xf bound_ctrl:1
	v_mov_b32_dpp v31, v29 quad_perm:[1,0,3,2] row_mask:0xf bank_mask:0xf bound_ctrl:1
	v_pk_add_f32 v[28:29], v[28:29], v[30:31]
	s_nop 1
	v_mov_b32_dpp v30, v28 quad_perm:[2,3,0,1] row_mask:0xf bank_mask:0xf bound_ctrl:1
	v_mov_b32_dpp v31, v29 quad_perm:[2,3,0,1] row_mask:0xf bank_mask:0xf bound_ctrl:1
	v_pk_add_f32 v[28:29], v[28:29], v[30:31]
	s_nop 1
	v_mov_b32_dpp v30, v28 row_half_mirror row_mask:0xf bank_mask:0xf bound_ctrl:1
	v_mov_b32_dpp v31, v29 row_half_mirror row_mask:0xf bank_mask:0xf bound_ctrl:1
	s_and_saveexec_b64 s[48:49], s[4:5]
	s_cbranch_execz .LBB0_1789
	v_pk_add_f32 v[28:29], v[28:29], v[30:31]
	v_add_co_u32_e32 v30, vcc, 0x48704000, v84
	s_nop 1
	v_addc_co_u32_e32 v31, vcc, 0, v85, vcc
	global_store_dwordx2 v[30:31], v[28:29], off

; __device__ __forceinline__ void rwkv_scan_phase(Frame& F, const bf16* RKV, const float* WAG, const bf16* AGB, const float* k_k, const float* k_a, const float* r_k, bf16* Y, float* BS, float* ST2) {
;     ...
;             ST_PROC(RA, 0);
;             __syncthreads();
;             for (int ci = 0; ci < NCH; ci += 2) {
;                 if (ci >= 1) ST_FLUSH(ci - 1);
;                 if (ci + 2 < NCH) ST_LOAD(RA, ci + 2);
;                 ST_PROC(RB, ci + 1);
;                 __syncthreads();
.LBB0_1797:
	s_or_b64 exec, exec, s[60:61]
	v_add_f32_e32 v181, v181, v182
	v_rsq_f32_e32 v181, v181
	ds_write_b128 v172, v[28:31] offset:45056
	ds_write_b128 v172, v[24:27] offset:53248
	ds_write_b128 v172, v[32:35] offset:61440
	v_max_f32_e64 v28, -v181, s35
	v_pk_mul_f32 v[30:31], v[142:143], v[28:29] op_sel_hi:[1,0]
	v_pk_mul_f32 v[28:29], v[144:145], v[28:29] op_sel_hi:[1,0]
	ds_write_b128 v178, v[28:31]
	v_pk_mul_f32 v[30:31], v[30:31], v[140:141] neg_lo:[1,0] neg_hi:[1,0]
	v_pk_mul_f32 v[28:29], v[28:29], v[138:139] neg_lo:[1,0] neg_hi:[1,0]
	ds_write_b128 v179, v[28:31]
	s_and_saveexec_b64 s[60:61], s[8:9]
	v_lshlrev_b32_e32 v28, 16, v64
	v_and_b32_e32 v29, 0xffff0000, v64
	v_lshlrev_b32_e32 v30, 16, v65
	v_and_b32_e32 v31, 0xffff0000, v65
	ds_write_b128 v180, v[28:31]
	s_or_b64 exec, exec, s[60:61]
	s_waitcnt lgkmcnt(0)
	s_barrier
	s_cmp_eq_u32 s81, 0
	s_cbranch_scc1 .Lctb_idle
	s_and_b32 s92, s81, 0x7fffffff
	v_mul_lo_u32 v243, v241, s92
	v_lshl_add_u32 v240, v242, 4, v243
	s_cmp_eq_u32 s32, 1
	s_cbranch_scc0 .Lctb_w0
	s_waitcnt vmcnt(10)
	s_branch .Lctb_wd

; __device__ __forceinline__ void rwkv_scan_phase(Frame& F, const bf16* RKV, const float* WAG, const bf16* AGB, const float* k_k, const float* k_a, const float* r_k, bf16* Y, float* BS, float* ST2) {
;     ...
;             constexpr int NCH = SEQ / SC_T;
;             v2u RAh[2][4], RBh[2][4]; f32x4 RAw[2], RBw[2];
;             ST_LOAD(RA, 0); ST_LOAD(RB, 1);
;             ST_PROC(RA, 0);
;             __syncthreads();
;             for (int ci = 0; ci < NCH; ci += 2) {
;                 if (ci >= 1) ST_FLUSH(ci - 1);
;                 if (ci + 2 < NCH) ST_LOAD(RA, ci + 2);
;                 ST_PROC(RB, ci + 1);
;                 __syncthreads();
;                 ST_FLUSH(ci);
;                 if (ci + 3 < NCH) ST_LOAD(RB, ci + 3);
;                 if (ci + 2 < NCH) ST_PROC(RA, ci + 2);
;                 __syncthreads();
.Lctby_end:
.Lctb_fin:
	s_mov_b64 s[78:79], s[70:71]
	s_mov_b32 s81, s69
	s_mov_b32 s32, 0
	ds_read_b128 v[28:31], v168
	v_add_co_u32_e32 v34, vcc, 0x49140000, v86
	s_waitcnt lgkmcnt(0)
	v_cvt_pk_bf16_f32 v32, v28, v29
	v_cvt_pk_bf16_f32 v33, v30, v31
	v_mul_f32_e32 v139, v31, v31
	v_addc_co_u32_e32 v35, vcc, 0, v87, vcc
	global_store_dwordx2 v[34:35], v[32:33], off
	v_mul_f32_e32 v33, v28, v28
	v_mul_f32_e32 v35, v29, v29
	v_mul_f32_e32 v87, v30, v30
	v_mov_b32_e32 v32, v28
	v_mov_b32_e32 v34, v29
	v_mov_b32_e32 v86, v30
	v_mov_b32_e32 v138, v31
	v_pk_add_f32 v[28:29], v[32:33], v[34:35]
	v_pk_add_f32 v[30:31], v[86:87], v[138:139]
	s_nop 0
	v_pk_add_f32 v[28:29], v[28:29], v[30:31]
	s_nop 1
	v_mov_b32_dpp v30, v28 quad_perm:[1,0,3,2] row_mask:0xf bank_mask:0xf bound_ctrl:1
	v_mov_b32_dpp v31, v29 quad_perm:[1,0,3,2] row_mask:0xf bank_mask:0xf bound_ctrl:1
	v_pk_add_f32 v[28:29], v[28:29], v[30:31]
	s_nop 1
	v_mov_b32_dpp v30, v28 quad_perm:[2,3,0,1] row_mask:0xf bank_mask:0xf bound_ctrl:1
	v_mov_b32_dpp v31, v29 quad_perm:[2,3,0,1] row_mask:0xf bank_mask:0xf bound_ctrl:1
	v_pk_add_f32 v[28:29], v[28:29], v[30:31]
	s_nop 1
	v_mov_b32_dpp v30, v28 row_half_mirror row_mask:0xf bank_mask:0xf bound_ctrl:1
	v_mov_b32_dpp v31, v29 row_half_mirror row_mask:0xf bank_mask:0xf bound_ctrl:1
	s_and_saveexec_b64 s[60:61], s[4:5]
	s_cbranch_execz .LBB0_1802
	v_pk_add_f32 v[28:29], v[28:29], v[30:31]
	v_add_co_u32_e32 v30, vcc, 0x48708000, v84
	s_nop 1
	v_addc_co_u32_e32 v31, vcc, 0, v85, vcc
	global_store_dwordx2 v[30:31], v[28:29], off
	s_or_b64 exec, exec, s[60:61]
	s_cmp_gt_u32 s58, 60
	s_cbranch_scc0 .LBB0_1803

; #define LAS __attribute__((address_space(3)))
; __device__ __forceinline__ void conv_proc(f32x4 (&v)[2][8], const float* gain, int K, int Kp, int Np, int ilv, bf16* WT, LAS float* scr, int item, int lane) {
;     const int nblk = Np / 64, kb = item / nblk, nb = item % nblk, k0 = 64 * kb, n0 = 64 * nb;
;     const int d0 = ilv ? (((n0 % ilv) >> 7) * 256 + (n0 / ilv) * 128 + ((n0 % ilv) & 127)) : n0;
;     const int kr = lane >> 3, n4 = lane & 7;
;     if (gain) {
; #pragma unroll
;         for (int i = 0; i < 8; ++i) { const int k = k0 + 8 * i + kr; const float g = k < K ? gain[k] : 0.f; v[0][i] *= g; v[1][i] *= g; } }
.LBB0_1812:
.Lctd_dloop:
	s_cmp_eq_u32 s81, 0
	s_cbranch_scc1 .Lctd_idle
	s_and_b32 s92, s81, 0x7fffffff
	v_mul_lo_u32 v243, v241, s92
	v_lshl_add_u32 v240, v242, 4, v243
	s_waitcnt vmcnt(0)
	s_bitcmp0_b32 s81, 31
	s_cbranch_scc1 .Lctd_nogain
	v_pk_mul_f32 v[188:189], v[188:189], v[220:221] op_sel_hi:[1,0]
	v_pk_mul_f32 v[190:191], v[190:191], v[220:221] op_sel_hi:[1,0]
	v_pk_mul_f32 v[192:193], v[192:193], v[220:221] op_sel:[0,1] op_sel_hi:[1,1]
	v_pk_mul_f32 v[194:195], v[194:195], v[220:221] op_sel:[0,1] op_sel_hi:[1,1]
	v_pk_mul_f32 v[196:197], v[196:197], v[222:223] op_sel_hi:[1,0]
	v_pk_mul_f32 v[198:199], v[198:199], v[222:223] op_sel_hi:[1,0]
	v_pk_mul_f32 v[200:201], v[200:201], v[222:223] op_sel:[0,1] op_sel_hi:[1,1]
	v_pk_mul_f32 v[202:203], v[202:203], v[222:223] op_sel:[0,1] op_sel_hi:[1,1]
	v_pk_mul_f32 v[204:205], v[204:205], v[224:225] op_sel_hi:[1,0]
	v_pk_mul_f32 v[206:207], v[206:207], v[224:225] op_sel_hi:[1,0]
	v_pk_mul_f32 v[208:209], v[208:209], v[224:225] op_sel:[0,1] op_sel_hi:[1,1]
	v_pk_mul_f32 v[210:211], v[210:211], v[224:225] op_sel:[0,1] op_sel_hi:[1,1]
	v_pk_mul_f32 v[212:213], v[212:213], v[226:227] op_sel_hi:[1,0]
	v_pk_mul_f32 v[214:215], v[214:215], v[226:227] op_sel_hi:[1,0]
	v_pk_mul_f32 v[216:217], v[216:217], v[226:227] op_sel:[0,1] op_sel_hi:[1,1]
	v_pk_mul_f32 v[218:219], v[218:219], v[226:227] op_sel:[0,1] op_sel_hi:[1,1]

; __device__ __forceinline__ void rwkv_scan_phase(Frame& F, const bf16* RKV, const float* WAG, const bf16* AGB, const float* k_k, const float* k_a, const float* r_k, bf16* Y, float* BS, float* ST2) {
;     ...
;             constexpr int NCH = SEQ / SC_T;
;             v2u RAh[2][4], RBh[2][4]; f32x4 RAw[2], RBw[2];
;             ST_LOAD(RA, 0); ST_LOAD(RB, 1);
;             ST_PROC(RA, 0);
;             __syncthreads();
;             for (int ci = 0; ci < NCH; ci += 2) {
;                 if (ci >= 1) ST_FLUSH(ci - 1);
;                 if (ci + 2 < NCH) ST_LOAD(RA, ci + 2);
;                 ST_PROC(RB, ci + 1);
;                 __syncthreads();
;                 ST_FLUSH(ci);
;                 if (ci + 3 < NCH) ST_LOAD(RB, ci + 3);
;                 if (ci + 2 < NCH) ST_PROC(RA, ci + 2);
;                 __syncthreads();
;             }
;             ST_FLUSH(NCH - 1);
.Lctdy_end:
.Lctd_fin:
	s_mov_b64 s[78:79], s[70:71]
	s_mov_b32 s81, s69
	s_mov_b32 s32, 0
	s_cmp_lg_u32 s81, 0
	s_cbranch_scc1 .Lctd_dloop
	ds_read_b128 v[0:3], v169
	v_lshl_add_u64 v[4:5], s[44:45], 1, v[106:107]
	s_lshl_b32 s0, s0, 1
	v_lshl_add_u64 v[4:5], v[4:5], 0, s[0:1]
	s_waitcnt lgkmcnt(0)
	v_cvt_pk_bf16_f32 v6, v0, v1
	v_cvt_pk_bf16_f32 v7, v2, v3
	v_lshl_add_u64 v[4:5], v[4:5], 0, v[92:93]
	global_store_dwordx2 v[4:5], v[6:7], off
	v_mul_f32_e32 v5, v0, v0
	v_mul_f32_e32 v7, v1, v1
	v_mul_f32_e32 v9, v2, v2
	v_mul_f32_e32 v11, v3, v3
	v_mov_b32_e32 v4, v0
	v_mov_b32_e32 v6, v1
	v_mov_b32_e32 v8, v2
	v_mov_b32_e32 v10, v3
	v_pk_add_f32 v[0:1], v[4:5], v[6:7]
	v_pk_add_f32 v[2:3], v[8:9], v[10:11]
	s_nop 0
	v_pk_add_f32 v[0:1], v[0:1], v[2:3]
	s_nop 1
	v_mov_b32_dpp v2, v0 quad_perm:[1,0,3,2] row_mask:0xf bank_mask:0xf bound_ctrl:1
	v_mov_b32_dpp v3, v1 quad_perm:[1,0,3,2] row_mask:0xf bank_mask:0xf bound_ctrl:1
	v_pk_add_f32 v[0:1], v[0:1], v[2:3]
	s_nop 1
	v_mov_b32_dpp v2, v0 quad_perm:[2,3,0,1] row_mask:0xf bank_mask:0xf bound_ctrl:1
	v_mov_b32_dpp v3, v1 quad_perm:[2,3,0,1] row_mask:0xf bank_mask:0xf bound_ctrl:1
	v_pk_add_f32 v[0:1], v[0:1], v[2:3]
	s_nop 1
	v_mov_b32_dpp v2, v0 row_half_mirror row_mask:0xf bank_mask:0xf bound_ctrl:1
	v_mov_b32_dpp v3, v1 row_half_mirror row_mask:0xf bank_mask:0xf bound_ctrl:1
	s_and_saveexec_b64 s[6:7], s[4:5]
	s_cbranch_execz .LBB0_1687
	v_lshl_add_u64 v[4:5], s[46:47], 0, v[104:105]
	v_lshlrev_b64 v[4:5], 9, v[4:5]
	v_lshl_add_u64 v[4:5], s[20:21], 0, v[4:5]
	s_lshl_b32 s0, s33, 2
	v_lshl_add_u64 v[4:5], v[4:5], 0, s[0:1]
	s_lshl_b32 s0, s54, 2
	v_lshl_add_u64 v[4:5], v[4:5], 0, s[0:1]
	v_pk_add_f32 v[0:1], v[0:1], v[2:3]
	global_store_dwordx2 v[4:5], v[0:1], off
	s_branch .LBB0_1687
